# attention item prologue: second K/V tile's loads issued with the first tile's (one round trip instead of two); stray full drain between the MLA Q loads and K/V loads removed
# baseline (speedup 1.0000x reference)
; template <int DQK, bool STATIC>
; DI void attn_item8(const bf16_t* __restrict__ Q, const bf16_t* __restrict__ Kp, const bf16_t* __restrict__ Vt, int nkeys, char* lds,
;                   const bf16_t* __restrict__ Pg, bf16_t* __restrict__ Yg  , float mfix) {
;     ...
;   for (int ks = 0; ks < NQS; ++ks) qf[ks] = *(const bf16x8*)(Q + (size_t)(32 * w + l31) * DQK + 16 * ks + 8 * h);
;   f32x16 o[2];
; #pragma unroll
;   for (int d = 0; d < 2; ++d)
; #pragma unroll
;     for (int e = 0; e < 16; ++e) o[d][e] = 0.f;
;   float m_run = STATIC ? mfix : -1e30f, l_run = 0.f;
;   u32x4 rk[NKC], rv[1];
;   int koffg[NKC], koffl[NKC];
; #pragma unroll
;   for (int i = 0; i < NKC; ++i) { const int c = tid + 512 * i; const int key = c / KCH, part = c % KCH; koffg[i] = (c < 64 * KCH) ? c * 8 : 0; koffl[i] = (c < 64 * KCH) ? key * KSTR + part * 16 : -1; }
;   const int vdv0 = tid >> 3, vpart = tid & 7;
;   const bf16_t* vg = Vt + (size_t)vdv0 * T + vpart * 8;
;   const int voffl = KBUF + vdv0 * VSTR + vpart * 16;
;   const int nt = nkeys >> 6;
; #pragma unroll
;   for (int i = 0; i < NKC; ++i) rk[i] = *(const u32x4*)(Kp + koffg[i]);
; #pragma unroll
;   for (int i = 0; i < 1; ++i) rv[i] = *(const u32x4*)(vg + (size_t)i * 32 * T);
; #pragma unroll
;   for (int i = 0; i < NKC; ++i) if (koffl[i] >= 0) *(u32x4*)(lds + koffl[i]) = rk[i];
; #pragma unroll
;   for (int i = 0; i < 1; ++i) { u32x2 a = {rv[i].x, rv[i].y}, b = {rv[i].z, rv[i].w}; *(u32x2*)(lds + voffl + i * 32 * VSTR) = a; *(u32x2*)(lds + voffl + i * 32 * VSTR + 8) = b; }
;   {
; #pragma unroll
;     for (int i = 0; i < NKC; ++i) rk[i] = *(const u32x4*)(Kp + (size_t)64 * DQK + koffg[i]);
;     rv[0] = *(const u32x4*)(vg + 64);
; #pragma unroll
;     for (int i = 0; i < NKC; ++i) if (koffl[i] >= 0) *(u32x4*)(lds + BUF + koffl[i]) = rk[i];
;     { u32x2 a = {rv[0].x, rv[0].y}, b = {rv[0].z, rv[0].w}; *(u32x2*)(lds + BUF + voffl) = a; *(u32x2*)(lds + BUF + voffl + 8) = b; }
;   }
;   __syncthreads();
.LBB0_37:
	s_cmp_gt_u32 s64, 63
	s_cselect_b64 s[20:21], -1, 0
	s_and_b32 s2, s64, 0x7ffffff8
	s_cmpk_lg_i32 s2, 0x80
	s_cselect_b64 s[34:35], -1, 0
	s_and_b32 s2, s18, 1
	v_readlane_b32 s18, v253, 5
	s_or_b32 s2, s2, s18
	s_mul_i32 s18, s2, 0x900
	s_and_b64 s[36:37], s[20:21], s[34:35]
	s_and_b32 s34, s19, 3
	s_add_u32 s20, s18, s4
	s_lshl_b32 s18, s2, 2
	s_or_b32 s35, s18, s34
	s_mul_i32 s69, s35, 0x900
	s_add_u32 s56, s69, s4
	s_addc_u32 s57, 0, s5
	s_mov_b64 s[4:5], -1
	s_and_b64 vcc, exec, s[36:37]
	s_mul_i32 s14, s20, 0x14c0
	s_cbranch_vccz .LBB0_75
	s_lshl_b32 s2, s2, 1
	s_lshr_b32 s4, s34, 1
	s_or_b32 s2, s2, s4
	s_lshl_b64 s[4:5], s[56:57], 7
	v_readlane_b32 s18, v255, 44
	s_add_u32 s76, s18, s4
	v_readlane_b32 s4, v255, 45
	s_addc_u32 s77, s4, s5
	s_mul_i32 s4, s2, 0x900
	s_add_u32 s4, s4, s48
	s_addc_u32 s5, 0, s49
	s_lshl_b64 s[4:5], s[4:5], 7
	v_readlane_b32 s18, v255, 47
	s_add_u32 s54, s18, s4
	v_readlane_b32 s4, v255, 48
	s_addc_u32 s55, s4, s5
	s_mul_i32 s2, s2, 0x48000
	v_readlane_b32 s4, v255, 49
	s_add_u32 s2, s4, s2
	v_readlane_b32 s4, v255, 50
	s_addc_u32 s4, s4, 0
	s_lshl_b32 s5, s48, 1
	s_add_u32 s50, s2, s5
	s_addc_u32 s51, s4, 0
	s_add_u32 s2, s42, s14
	s_addc_u32 s4, s43, 0
	s_lshl_b32 s5, s34, 7
	s_add_u32 s2, s2, s5
	s_addc_u32 s4, s4, 0
	s_add_u32 s36, s2, 0x8c0
	s_addc_u32 s37, s4, 0
	s_lshl_b32 s2, s20, 11
	v_readlane_b32 s4, v255, 31
	s_add_u32 s2, s4, s2
	v_readlane_b32 s4, v255, 32
	s_addc_u32 s4, s4, 0
	s_add_u32 s2, s2, s5
	s_addc_u32 s4, s4, 0
	s_add_u32 s40, s2, 0x200
	s_addc_u32 s41, s4, 0
	s_mov_b64 s[4:5], exec
	v_readlane_b32 s18, v255, 51
	v_readlane_b32 s19, v255, 52
	s_and_b64 s[18:19], s[4:5], s[18:19]
	s_xor_b64 s[4:5], s[18:19], s[4:5]
	s_mov_b64 exec, s[18:19]
	s_cbranch_execz .LBB0_54
	v_mov_b32_e32 v40, v196
	s_movk_i32 s2, 0xffe0
	v_ashrrev_i32_e32 v0, 1, v40
	v_bfi_b32 v188, s2, v0, v40
	v_ashrrev_i32_e32 v189, 31, v188
	v_bfe_u32 v187, v40, 5, 1
	v_lshlrev_b64 v[34:35], 7, v[188:189]
	v_lshl_add_u64 v[34:35], s[76:77], 0, v[34:35]
	v_lshlrev_b32_e32 v0, 4, v187
	v_lshl_add_u64 v[34:35], v[34:35], 0, v[0:1]
	v_ashrrev_i32_e32 v42, 3, v40
	v_and_b32_e32 v43, 7, v40
	v_mov_b64_e32 v[36:37], s[50:51]
	s_movk_i32 s2, 0x1200
	global_load_dwordx4 v[98:101], v[34:35], off offset:32
	global_load_dwordx4 v[102:105], v[34:35], off offset:64
	global_load_dwordx4 v[106:109], v[34:35], off offset:96
	v_mad_i64_i32 v[36:37], s[18:19], v42, s2, v[36:37]
	v_lshlrev_b32_e32 v38, 4, v43
	v_mov_b32_e32 v39, v1
	v_lshl_add_u64 v[122:123], v[36:37], 0, v[38:39]
	global_load_dwordx4 v[110:113], v[34:35], off
	s_nop 0
	global_load_dwordx4 v[34:37], v[122:123], off
	v_ashrrev_i32_e32 v38, 31, v40
	v_lshrrev_b32_e32 v38, 29, v38
	v_add_u32_e32 v38, v40, v38
	v_lshrrev_b32_e32 v39, 3, v38
	s_movk_i32 s2, 0x200
	v_lshlrev_b32_e32 v38, 3, v40
	v_cmp_gt_i32_e32 vcc, s2, v40
	v_add_lshl_u32 v39, v39, v40, 4
	s_nop 0
	v_cndmask_b32_e32 v38, 0, v38, vcc
	v_cndmask_b32_e32 v126, -1, v39, vcc
	v_cmp_lt_i32_e64 s[44:45], -1, v126
	v_cmp_gt_i32_e32 vcc, 0, v126
	v_ashrrev_i32_e32 v39, 31, v38
	s_mov_b64 s[18:19], 0x2000
	v_lshl_add_u64 v[124:125], v[38:39], 1, s[54:55]
	v_lshl_add_u64 v[114:115], v[124:125], 0, s[18:19]
	global_load_dwordx4 v[114:117], v[114:115], off
	global_load_dwordx4 v[118:121], v[122:123], off offset:128
	s_and_saveexec_b64 s[18:19], vcc
	s_xor_b64 s[18:19], exec, s[18:19]
	s_or_saveexec_b64 s[18:19], s[18:19]
	v_add_u32_e32 v41, 0, v126
	s_xor_b64 exec, exec, s[18:19]
	s_cbranch_execz .LBB0_41
	v_lshl_add_u64 v[44:45], v[38:39], 1, s[54:55]
	global_load_dwordx4 v[44:47], v[44:45], off
	s_waitcnt vmcnt(0) lgkmcnt(0)
	ds_write_b128 v41, v[44:47]
.LBB0_41:
	s_or_b64 exec, exec, s[18:19]
	s_movk_i32 s2, 0x88
	v_mul_lo_u32 v42, v42, s2
	v_lshl_add_u32 v127, v43, 4, v42
	v_add_u32_e32 v42, 0, v127
	v_add_u32_e32 v43, 0x2400, v42
	v_lshl_add_u64 v[124:125], v[38:39], 1, s[54:55]
	s_waitcnt vmcnt(0) lgkmcnt(0)
	ds_write2_b64 v43, v[34:35], v[36:37] offset1:1
	v_add_co_u32_e32 v34, vcc, 0x2000, v124
	s_nop 1
	v_addc_co_u32_e32 v35, vcc, 0, v125, vcc
	s_and_saveexec_b64 s[18:19], s[44:45]
	s_cbranch_execz .LBB0_43
	s_waitcnt vmcnt(0) lgkmcnt(0)
	ds_write_b128 v41, v[114:117] offset:17920

; template <int DQK, bool STATIC>
; DI void attn_item8(const bf16_t* __restrict__ Q, const bf16_t* __restrict__ Kp, const bf16_t* __restrict__ Vt, int nkeys, char* lds,
;                   const bf16_t* __restrict__ Pg, bf16_t* __restrict__ Yg  , float mfix) {
;     ...
;   for (int ks = 0; ks < NQS; ++ks) qf[ks] = *(const bf16x8*)(Q + (size_t)(32 * w + l31) * DQK + 16 * ks + 8 * h);
;   f32x16 o[2];
; #pragma unroll
;   for (int d = 0; d < 2; ++d)
; #pragma unroll
;     for (int e = 0; e < 16; ++e) o[d][e] = 0.f;
;   float m_run = STATIC ? mfix : -1e30f, l_run = 0.f;
;   u32x4 rk[NKC], rv[1];
;   int koffg[NKC], koffl[NKC];
; #pragma unroll
;   for (int i = 0; i < NKC; ++i) { const int c = tid + 512 * i; const int key = c / KCH, part = c % KCH; koffg[i] = (c < 64 * KCH) ? c * 8 : 0; koffl[i] = (c < 64 * KCH) ? key * KSTR + part * 16 : -1; }
;   const int vdv0 = tid >> 3, vpart = tid & 7;
;   const bf16_t* vg = Vt + (size_t)vdv0 * T + vpart * 8;
;   const int voffl = KBUF + vdv0 * VSTR + vpart * 16;
;   const int nt = nkeys >> 6;
; #pragma unroll
;   for (int i = 0; i < NKC; ++i) rk[i] = *(const u32x4*)(Kp + koffg[i]);
; #pragma unroll
;   for (int i = 0; i < 1; ++i) rv[i] = *(const u32x4*)(vg + (size_t)i * 32 * T);
; #pragma unroll
;   for (int i = 0; i < NKC; ++i) if (koffl[i] >= 0) *(u32x4*)(lds + koffl[i]) = rk[i];
; #pragma unroll
;   for (int i = 0; i < 1; ++i) { u32x2 a = {rv[i].x, rv[i].y}, b = {rv[i].z, rv[i].w}; *(u32x2*)(lds + voffl + i * 32 * VSTR) = a; *(u32x2*)(lds + voffl + i * 32 * VSTR + 8) = b; }
;   {
; #pragma unroll
;     for (int i = 0; i < NKC; ++i) rk[i] = *(const u32x4*)(Kp + (size_t)64 * DQK + koffg[i]);
;     rv[0] = *(const u32x4*)(vg + 64);
; #pragma unroll
;     for (int i = 0; i < NKC; ++i) if (koffl[i] >= 0) *(u32x4*)(lds + BUF + koffl[i]) = rk[i];
;     { u32x2 a = {rv[0].x, rv[0].y}, b = {rv[0].z, rv[0].w}; *(u32x2*)(lds + BUF + voffl) = a; *(u32x2*)(lds + BUF + voffl + 8) = b; }
;   }
;   __syncthreads();
.LBB0_75:
	s_andn2_b64 vcc, exec, s[4:5]
	s_cbranch_vccnz .LBB0_31
	s_mul_i32 s2, s57, 0xc0
	s_mul_hi_u32 s4, s56, 0xc0
	s_add_i32 s4, s4, s2
	s_mul_i32 s2, s56, 0xc0
	v_readlane_b32 s5, v255, 38
	s_add_u32 s50, s5, s2
	v_readlane_b32 s2, v255, 39
	s_addc_u32 s51, s2, s4
	s_add_i32 s2, s69, s48
	s_mulk_i32 s2, 0xc0
	v_readlane_b32 s4, v255, 40
	s_add_u32 s56, s4, s2
	v_readlane_b32 s2, v255, 41
	s_addc_u32 s57, s2, 0
	s_mul_i32 s35, s35, 0x48000
	v_readlane_b32 s2, v255, 42
	s_add_u32 s2, s2, s35
	v_readlane_b32 s4, v255, 43
	s_addc_u32 s4, s4, 0
	s_lshl_b32 s5, s48, 1
	s_add_u32 s54, s2, s5
	s_addc_u32 s55, s4, 0
	s_add_u32 s2, s42, s14
	s_addc_u32 s4, s43, 0
	s_lshl_b32 s5, s34, 7
	s_add_u32 s2, s2, s5
	s_addc_u32 s4, s4, 0
	s_add_u32 s36, s2, 0x2c0
	s_addc_u32 s37, s4, 0
	s_lshl_b32 s2, s20, 11
	v_readlane_b32 s4, v255, 31
	s_add_u32 s2, s4, s2
	v_readlane_b32 s4, v255, 32
	s_addc_u32 s4, s4, 0
	s_add_u32 s40, s2, s5
	s_addc_u32 s41, s4, 0
	s_mov_b64 s[4:5], exec
	v_readlane_b32 s18, v255, 53
	v_readlane_b32 s19, v255, 54
	s_and_b64 s[18:19], s[4:5], s[18:19]
	s_xor_b64 s[4:5], s[18:19], s[4:5]
	s_mov_b64 exec, s[18:19]
	s_cbranch_execz .LBB0_98
	v_mov_b32_e32 v42, v196
	s_movk_i32 s2, 0xffe0
	s_waitcnt lgkmcnt(0)
	v_ashrrev_i32_e32 v0, 1, v42
	v_bfe_u32 v187, v42, 5, 1
	v_bfi_b32 v188, s2, v0, v42
	v_mov_b64_e32 v[34:35], s[50:51]
	s_movk_i32 s2, 0xc0
	v_mad_i64_i32 v[34:35], s[18:19], v188, s2, v[34:35]
	v_lshlrev_b32_e32 v0, 4, v187
	v_add_u32_e32 v44, 0x200, v42
	s_movk_i32 s2, 0x100
	v_lshl_add_u64 v[38:39], v[34:35], 0, v[0:1]
	v_lshlrev_b32_e32 v34, 3, v44
	v_cmp_gt_i32_e32 vcc, s2, v42
	global_load_dwordx4 v[98:101], v[38:39], off offset:32
	global_load_dwordx4 v[102:105], v[38:39], off offset:64
	global_load_dwordx4 v[106:109], v[38:39], off offset:96
	global_load_dwordx4 v[110:113], v[38:39], off offset:128
	v_cndmask_b32_e32 v134, 0, v34, vcc
	v_ashrrev_i32_e32 v45, 3, v42
	v_and_b32_e32 v46, 7, v42
	v_ashrrev_i32_e32 v135, 31, v134
	v_mov_b64_e32 v[40:41], s[54:55]
	s_movk_i32 s2, 0x1200
	v_lshl_add_u64 v[34:35], v[134:135], 1, s[56:57]
	v_mad_i64_i32 v[40:41], s[18:19], v45, s2, v[40:41]
	v_lshlrev_b32_e32 v48, 4, v46
	v_mov_b32_e32 v49, v1
	global_load_dwordx4 v[114:117], v[38:39], off offset:160
	s_nop 0
	global_load_dwordx4 v[34:37], v[34:35], off
	v_lshl_add_u64 v[136:137], v[40:41], 0, v[48:49]
	global_load_dwordx4 v[118:121], v[38:39], off
	s_nop 0
	global_load_dwordx4 v[38:41], v[136:137], off
	s_mov_b32 s2, 0x2aaaaaab
	v_mul_hi_i32 v43, v42, s2
	v_lshrrev_b32_e32 v47, 31, v43
	v_lshrrev_b32_e32 v43, 1, v43
	v_add_u32_e32 v43, v43, v47
	v_lshlrev_b32_e32 v47, 3, v42
	v_cmp_gt_i32_e64 s[44:45], s58, v42
	v_add_lshl_u32 v43, v43, v42, 4
	s_nop 0
	v_cndmask_b32_e64 v138, 0, v47, s[44:45]
	v_cndmask_b32_e64 v140, -1, v43, s[44:45]
	v_ashrrev_i32_e32 v139, 31, v138
	v_cmp_lt_i32_e64 s[44:45], -1, v140
	v_add_u32_e32 v43, 0, v140
	s_add_u32 s18, s56, 0x3000
	s_addc_u32 s19, s57, 0
	v_lshl_add_u64 v[122:123], v[138:139], 1, s[18:19]
	v_lshl_add_u64 v[126:127], v[134:135], 1, s[18:19]
	global_load_dwordx4 v[122:125], v[122:123], off
	global_load_dwordx4 v[126:129], v[126:127], off
	global_load_dwordx4 v[130:133], v[136:137], off offset:128
	s_and_saveexec_b64 s[18:19], s[44:45]
	s_cbranch_execz .LBB0_79
	v_lshl_add_u64 v[48:49], v[138:139], 1, s[56:57]
	global_load_dwordx4 v[48:51], v[48:49], off
	s_waitcnt vmcnt(0) lgkmcnt(0)
	ds_write_b128 v43, v[48:51]

; template <int DQK, bool STATIC>
; DI void attn_item8(const bf16_t* __restrict__ Q, const bf16_t* __restrict__ Kp, const bf16_t* __restrict__ Vt, int nkeys, char* lds,
;                   const bf16_t* __restrict__ Pg, bf16_t* __restrict__ Yg  , float mfix) {
;     ...
;     for (int i = 0; i < NKC; ++i) rk[i] = *(const u32x4*)(Kp + (size_t)64 * DQK + koffg[i]);
;     rv[0] = *(const u32x4*)(vg + 64);
; #pragma unroll
;     for (int i = 0; i < NKC; ++i) if (koffl[i] >= 0) *(u32x4*)(lds + BUF + koffl[i]) = rk[i];
;     { u32x2 a = {rv[0].x, rv[0].y}, b = {rv[0].z, rv[0].w}; *(u32x2*)(lds + BUF + voffl) = a; *(u32x2*)(lds + BUF + voffl + 8) = b; }
.LBB0_81:
	s_or_b64 exec, exec, s[18:19]
	s_movk_i32 s2, 0x88
	s_waitcnt vmcnt(0) lgkmcnt(0)
	v_mul_lo_u32 v34, v45, s2
	v_lshl_add_u32 v142, v46, 4, v34
	s_add_u32 s18, s56, 0x3000
	v_add_u32_e32 v34, 0, v142
	s_addc_u32 s19, s57, 0
	v_add_u32_e32 v35, 0x3400, v34
	v_lshl_add_u64 v[36:37], v[138:139], 1, s[18:19]
	ds_write2_b64 v35, v[38:39], v[40:41] offset1:1
	v_lshl_add_u64 v[36:37], v[134:135], 1, s[18:19]
	s_and_saveexec_b64 s[18:19], s[44:45]
	s_cbranch_execz .LBB0_83
	s_waitcnt vmcnt(0) lgkmcnt(0)
	ds_write_b128 v43, v[122:125] offset:22016
